# sample-panel skinny GEMMs: all operand loads issued up front (K=768/1024) or 5-8 k-steps in flight (K=2816) instead of one waited load per MFMA
# speedup vs baseline: 1.0266x; 1.0055x over previous
; template <class SEpi>
; __device__ __forceinline__ void sample_gemm(LAS unsigned char* lds, const bf16_t* A, const bf16_t* Bt, int K, const SEpi& E, int wave, int lane) {
;     ...
;         for (int k0 = 0; k0 < nks; k0 += 4) {
;             bf16x8 af[4], bf[4][4];
; #pragma unroll
;             for (int u = 0; u < 4; ++u) { const int ks = (k0 + u < nks) ? k0 + u : k0;
;                 af[u] = *(const bf16x8*)(ap + 32 * ks);
; #pragma unroll
;                 for (int c = 0; c < 4; ++c) bf[u][c] = *(const bf16x8*)(bp + (size_t)(16 * c) * K + 32 * ks); }
; #pragma unroll
;             for (int u = 0; u < 4; ++u) if (k0 + u < nks) {
; #pragma unroll
;                 for (int c = 0; c < 4; ++c) acc[c] = __builtin_amdgcn_mfma_f32_16x16x32_bf16(bf[u][c], af[u], acc[c], 0, 0, 0); }
;         }
.LBB0_350:
	v_lshl_add_u64 v[28:29], v[24:25], 0, s[46:47]
	v_lshl_add_u64 v[26:27], v[22:23], 0, s[46:47]
	s_mov_b32 s6, 0x2c00000
	v_add_co_u32_e32 v64, vcc, s6, v28
	s_nop 1
	v_addc_co_u32_e32 v65, vcc, 0, v29, vcc
	s_mov_b32 s6, 0x2c16000
	v_add_co_u32_e32 v70, vcc, s6, v28
	s_nop 1
	v_addc_co_u32_e32 v71, vcc, 0, v29, vcc
	s_mov_b32 s6, 0x2c2c000
	v_add_co_u32_e32 v248, vcc, s6, v28
	s_nop 1
	v_addc_co_u32_e32 v249, vcc, 0, v29, vcc
	s_mov_b32 s6, 0x2c42000
	v_add_co_u32_e32 v250, vcc, s6, v28
	s_nop 1
	v_addc_co_u32_e32 v251, vcc, 0, v29, vcc
	global_load_dwordx4 v[36:39], v[26:27], off offset:-128
	global_load_dwordx4 v[40:43], v[64:65], off
	global_load_dwordx4 v[44:47], v[70:71], off
	global_load_dwordx4 v[48:51], v[248:249], off
	global_load_dwordx4 v[52:55], v[250:251], off
	global_load_dwordx4 v[56:59], v[26:27], off offset:-64
	global_load_dwordx4 v[60:63], v[64:65], off offset:64
	global_load_dwordx4 v[96:99], v[70:71], off offset:64
	global_load_dwordx4 v[100:103], v[248:249], off offset:64
	global_load_dwordx4 v[104:107], v[250:251], off offset:64
	global_load_dwordx4 v[108:111], v[26:27], off
	global_load_dwordx4 v[150:153], v[64:65], off offset:128
	global_load_dwordx4 v[166:169], v[70:71], off offset:128
	global_load_dwordx4 v[170:173], v[248:249], off offset:128
	global_load_dwordx4 v[174:177], v[250:251], off offset:128
	global_load_dwordx4 v[178:181], v[26:27], off offset:64
	global_load_dwordx4 v[182:185], v[64:65], off offset:192
	global_load_dwordx4 v[186:189], v[70:71], off offset:192
	global_load_dwordx4 v[196:199], v[248:249], off offset:192
	global_load_dwordx4 v[200:203], v[250:251], off offset:192
	global_load_dwordx4 v[206:209], v[26:27], off offset:128
	global_load_dwordx4 v[210:213], v[64:65], off offset:256
	global_load_dwordx4 v[214:217], v[70:71], off offset:256
	global_load_dwordx4 v[218:221], v[248:249], off offset:256
	global_load_dwordx4 v[222:225], v[250:251], off offset:256
	global_load_dwordx4 v[226:229], v[26:27], off offset:192
	global_load_dwordx4 v[230:233], v[64:65], off offset:320
	global_load_dwordx4 v[234:237], v[70:71], off offset:320
	global_load_dwordx4 v[238:241], v[248:249], off offset:320
	global_load_dwordx4 v[244:247], v[250:251], off offset:320
	s_waitcnt vmcnt(25)
	v_mfma_f32_16x16x32_bf16 v[0:3], v[40:43], v[36:39], v[0:3]
	v_mfma_f32_16x16x32_bf16 v[4:7], v[44:47], v[36:39], v[4:7]
	v_mfma_f32_16x16x32_bf16 v[8:11], v[48:51], v[36:39], v[8:11]
	v_mfma_f32_16x16x32_bf16 v[12:15], v[52:55], v[36:39], v[12:15]
	global_load_dwordx4 v[36:39], v[26:27], off offset:256
	global_load_dwordx4 v[40:43], v[64:65], off offset:384
	global_load_dwordx4 v[44:47], v[70:71], off offset:384
	global_load_dwordx4 v[48:51], v[248:249], off offset:384
	global_load_dwordx4 v[52:55], v[250:251], off offset:384
	s_waitcnt vmcnt(25)
	v_mfma_f32_16x16x32_bf16 v[0:3], v[60:63], v[56:59], v[0:3]
	v_mfma_f32_16x16x32_bf16 v[4:7], v[96:99], v[56:59], v[4:7]
	v_mfma_f32_16x16x32_bf16 v[8:11], v[100:103], v[56:59], v[8:11]
	v_mfma_f32_16x16x32_bf16 v[12:15], v[104:107], v[56:59], v[12:15]
	global_load_dwordx4 v[56:59], v[26:27], off offset:320
	global_load_dwordx4 v[60:63], v[64:65], off offset:448
	global_load_dwordx4 v[96:99], v[70:71], off offset:448
	global_load_dwordx4 v[100:103], v[248:249], off offset:448
	global_load_dwordx4 v[104:107], v[250:251], off offset:448
	s_waitcnt vmcnt(25)
	v_mfma_f32_16x16x32_bf16 v[0:3], v[150:153], v[108:111], v[0:3]
	v_mfma_f32_16x16x32_bf16 v[4:7], v[166:169], v[108:111], v[4:7]
	v_mfma_f32_16x16x32_bf16 v[8:11], v[170:173], v[108:111], v[8:11]
	v_mfma_f32_16x16x32_bf16 v[12:15], v[174:177], v[108:111], v[12:15]
	global_load_dwordx4 v[108:111], v[26:27], off offset:384
	global_load_dwordx4 v[150:153], v[64:65], off offset:512
	global_load_dwordx4 v[166:169], v[70:71], off offset:512
	global_load_dwordx4 v[170:173], v[248:249], off offset:512
	global_load_dwordx4 v[174:177], v[250:251], off offset:512
	s_waitcnt vmcnt(25)
	v_mfma_f32_16x16x32_bf16 v[0:3], v[182:185], v[178:181], v[0:3]
	v_mfma_f32_16x16x32_bf16 v[4:7], v[186:189], v[178:181], v[4:7]
	v_mfma_f32_16x16x32_bf16 v[8:11], v[196:199], v[178:181], v[8:11]
	v_mfma_f32_16x16x32_bf16 v[12:15], v[200:203], v[178:181], v[12:15]
	global_load_dwordx4 v[178:181], v[26:27], off offset:448
	global_load_dwordx4 v[182:185], v[64:65], off offset:576
	global_load_dwordx4 v[186:189], v[70:71], off offset:576
	global_load_dwordx4 v[196:199], v[248:249], off offset:576
	global_load_dwordx4 v[200:203], v[250:251], off offset:576
	s_waitcnt vmcnt(25)
	v_mfma_f32_16x16x32_bf16 v[0:3], v[210:213], v[206:209], v[0:3]
	v_mfma_f32_16x16x32_bf16 v[4:7], v[214:217], v[206:209], v[4:7]
	v_mfma_f32_16x16x32_bf16 v[8:11], v[218:221], v[206:209], v[8:11]
	v_mfma_f32_16x16x32_bf16 v[12:15], v[222:225], v[206:209], v[12:15]
	global_load_dwordx4 v[206:209], v[26:27], off offset:512
	global_load_dwordx4 v[210:213], v[64:65], off offset:640
	global_load_dwordx4 v[214:217], v[70:71], off offset:640
	global_load_dwordx4 v[218:221], v[248:249], off offset:640
	global_load_dwordx4 v[222:225], v[250:251], off offset:640
	s_waitcnt vmcnt(25)
	v_mfma_f32_16x16x32_bf16 v[0:3], v[230:233], v[226:229], v[0:3]
	v_mfma_f32_16x16x32_bf16 v[4:7], v[234:237], v[226:229], v[4:7]
	v_mfma_f32_16x16x32_bf16 v[8:11], v[238:241], v[226:229], v[8:11]
	v_mfma_f32_16x16x32_bf16 v[12:15], v[244:247], v[226:229], v[12:15]
	s_waitcnt vmcnt(20)
	v_mfma_f32_16x16x32_bf16 v[0:3], v[40:43], v[36:39], v[0:3]
	v_mfma_f32_16x16x32_bf16 v[4:7], v[44:47], v[36:39], v[4:7]
	v_mfma_f32_16x16x32_bf16 v[8:11], v[48:51], v[36:39], v[8:11]
	v_mfma_f32_16x16x32_bf16 v[12:15], v[52:55], v[36:39], v[12:15]
	s_waitcnt vmcnt(15)
	v_mfma_f32_16x16x32_bf16 v[0:3], v[60:63], v[56:59], v[0:3]
	v_mfma_f32_16x16x32_bf16 v[4:7], v[96:99], v[56:59], v[4:7]
	v_mfma_f32_16x16x32_bf16 v[8:11], v[100:103], v[56:59], v[8:11]
	v_mfma_f32_16x16x32_bf16 v[12:15], v[104:107], v[56:59], v[12:15]
	s_waitcnt vmcnt(10)
	v_mfma_f32_16x16x32_bf16 v[0:3], v[150:153], v[108:111], v[0:3]
	v_mfma_f32_16x16x32_bf16 v[4:7], v[166:169], v[108:111], v[4:7]
	v_mfma_f32_16x16x32_bf16 v[8:11], v[170:173], v[108:111], v[8:11]
	v_mfma_f32_16x16x32_bf16 v[12:15], v[174:177], v[108:111], v[12:15]
	s_waitcnt vmcnt(5)
	v_mfma_f32_16x16x32_bf16 v[0:3], v[182:185], v[178:181], v[0:3]
	v_mfma_f32_16x16x32_bf16 v[4:7], v[186:189], v[178:181], v[4:7]
	v_mfma_f32_16x16x32_bf16 v[8:11], v[196:199], v[178:181], v[8:11]
	v_mfma_f32_16x16x32_bf16 v[12:15], v[200:203], v[178:181], v[12:15]
	s_waitcnt vmcnt(0)
	v_mfma_f32_16x16x32_bf16 v[0:3], v[210:213], v[206:209], v[0:3]
	v_mfma_f32_16x16x32_bf16 v[4:7], v[214:217], v[206:209], v[4:7]
	v_mfma_f32_16x16x32_bf16 v[8:11], v[218:221], v[206:209], v[8:11]
	v_mfma_f32_16x16x32_bf16 v[12:15], v[222:225], v[206:209], v[12:15]

;     __device__ __forceinline__ float apply(const f32x4 acc, int row, int col, int fq) const {
;         bf16_t* bp = xb + (size_t)row * D + col; const u32x2 r = *(const u32x2*)bp; f32x4 o;
;         o[0] = __uint_as_float(r.x << 16); o[1] = __uint_as_float(r.x & 0xffff0000u); o[2] = __uint_as_float(r.y << 16); o[3] = __uint_as_float(r.y & 0xffff0000u);
;         o += acc * scale;
; template <class SEpi>
; __device__ __forceinline__ void sample_gemm(LAS unsigned char* lds, const bf16_t* A, const bf16_t* Bt, int K, const SEpi& E, int wave, int lane) {
;     ...
;         const int rt = piece >> 4, cg = piece & 15, row = MP + 16 * rt + fr;
;         const bf16_t* ap = A + (size_t)row * K + wave * (K >> 3) + 8 * fq; const bf16_t* bp = Bt + (size_t)(64 * cg + fr) * K + wave * (K >> 3) + 8 * fq;
;         f32x4 acc[4];
; #pragma unroll
;         for (int c = 0; c < 4; ++c) acc[c] = (f32x4){0.f, 0.f, 0.f, 0.f};
; #pragma unroll 1
;         for (int k0 = 0; k0 < nks; k0 += 4) {
;             bf16x8 af[4], bf[4][4];
; #pragma unroll
;             for (int u = 0; u < 4; ++u) { const int ks = (k0 + u < nks) ? k0 + u : k0;
;                 af[u] = *(const bf16x8*)(ap + 32 * ks);
; #pragma unroll
;                 for (int c = 0; c < 4; ++c) bf[u][c] = *(const bf16x8*)(bp + (size_t)(16 * c) * K + 32 * ks); }
; #pragma unroll
;             for (int u = 0; u < 4; ++u) if (k0 + u < nks) {
; #pragma unroll
;                 for (int c = 0; c < 4; ++c) acc[c] = __builtin_amdgcn_mfma_f32_16x16x32_bf16(bf[u][c], af[u], acc[c], 0, 0, 0); }
;         }
;         asm volatile("s_nop 15\n\ts_nop 15" : "+v"(acc[0]), "+v"(acc[1]), "+v"(acc[2]), "+v"(acc[3]));
; #pragma unroll
;         for (int c = 0; c < 4; ++c) red[(wave * 4 + c) * 64 + lane] = acc[c];
;         __syncthreads();
;         if (wave < 4) {
;             f32x4 t = red[wave * 64 + lane];
; #pragma unroll
;             for (int w = 1; w < 8; ++w) t += red[(w * 4 + wave) * 64 + lane];
;             float q = E.apply(t, row, 64 * cg + 16 * wave + 4 * fq, fq);
;             if (SEpi::HAS_SSQ) { q += __shfl_xor(q, 16); q += __shfl_xor(q, 32); if (fq == 0) P[wave * 16 + fr] = q; }
;         }
;         __syncthreads();
;         if (SEpi::HAS_SSQ && wave == 0 && lane < 16) E.ssq_out[(size_t)(MP + 16 * rt + lane) * 16 + cg] = (P[lane] + P[16 + lane]) + (P[32 + lane] + P[48 + lane]);
;         __syncthreads();
.LBB0_801:
	s_and_b32 s26, s4, 15
	s_lshl_b32 s28, s26, 6
	v_or_b32_e32 v0, s28, v161
	v_mul_u32_u24_e32 v0, 0x300, v0
	v_lshlrev_b32_e32 v0, 1, v0
	v_lshl_add_u64 v[42:43], v[4:5], 0, v[0:1]
	v_add_co_u32_e32 v44, vcc, 0x6000, v42
	s_and_b32 s27, s4, -16
	s_nop 0
	v_addc_co_u32_e32 v45, vcc, 0, v43, vcc
	v_add_co_u32_e32 v46, vcc, 0xc000, v42
	s_addk_i32 s27, 0x4000
	s_nop 0
	v_addc_co_u32_e32 v47, vcc, 0, v43, vcc
	v_add_co_u32_e32 v48, vcc, 0x12000, v42
	v_or_b32_e32 v6, s27, v161
	s_movk_i32 s6, 0x600
	v_addc_co_u32_e32 v49, vcc, 0, v43, vcc
	v_mad_i64_i32 v[40:41], s[6:7], v6, s6, v[2:3]
	global_load_dwordx4 v[96:99], v[42:43], off
	global_load_dwordx4 v[100:103], v[44:45], off
	global_load_dwordx4 v[104:107], v[40:41], off
	global_load_dwordx4 v[108:111], v[46:47], off
	global_load_dwordx4 v[166:169], v[40:41], off offset:64
	global_load_dwordx4 v[170:173], v[48:49], off
	global_load_dwordx4 v[174:177], v[42:43], off offset:64
	s_and_b64 vcc, exec, s[44:45]
	global_load_dwordx4 v[178:181], v[46:47], off offset:64
	global_load_dwordx4 v[182:185], v[40:41], off offset:128
	global_load_dwordx4 v[186:189], v[44:45], off offset:64
	global_load_dwordx4 v[196:199], v[42:43], off offset:128
	global_load_dwordx4 v[200:203], v[48:49], off offset:64
	global_load_dwordx4 v[206:209], v[44:45], off offset:128
	global_load_dwordx4 v[210:213], v[46:47], off offset:128
	global_load_dwordx4 v[214:217], v[48:49], off offset:128
	s_waitcnt vmcnt(0)
	v_mfma_f32_16x16x32_bf16 v[16:19], v[100:103], v[104:107], 0
	v_mfma_f32_16x16x32_bf16 v[12:15], v[96:99], v[104:107], 0
	v_mfma_f32_16x16x32_bf16 v[24:27], v[108:111], v[104:107], 0
	v_mfma_f32_16x16x32_bf16 v[20:23], v[170:173], v[104:107], 0
	v_mfma_f32_16x16x32_bf16 v[24:27], v[178:181], v[166:169], v[24:27]
	v_mfma_f32_16x16x32_bf16 v[12:15], v[174:177], v[166:169], v[12:15]
	v_mfma_f32_16x16x32_bf16 v[16:19], v[186:189], v[166:169], v[16:19]
	v_mfma_f32_16x16x32_bf16 v[12:15], v[196:199], v[182:185], v[12:15]
	v_mfma_f32_16x16x32_bf16 v[20:23], v[200:203], v[166:169], v[20:23]
	v_mfma_f32_16x16x32_bf16 v[16:19], v[206:209], v[182:185], v[16:19]
	v_mfma_f32_16x16x32_bf16 v[24:27], v[210:213], v[182:185], v[24:27]
	v_mfma_f32_16x16x32_bf16 v[20:23], v[214:217], v[182:185], v[20:23]
	s_nop 7
	ds_write_b128 v10, v[12:15]
	s_nop 0
	ds_write_b128 v10, v[16:19] offset:1024
	s_nop 1
	ds_write_b128 v10, v[24:27] offset:2048
	s_nop 1
	ds_write_b128 v10, v[20:23] offset:3072
	s_waitcnt lgkmcnt(0)
	s_barrier
	s_cbranch_vccnz .LBB0_805
	ds_read_b128 v[12:15], v11
	ds_read_b128 v[16:19], v11 offset:4096
	v_ashrrev_i32_e32 v7, 31, v6
	v_or_b32_e32 v0, s28, v8
	v_lshlrev_b64 v[6:7], 11, v[6:7]
	v_lshl_add_u64 v[6:7], s[22:23], 0, v[6:7]
	s_waitcnt lgkmcnt(0)
	v_pk_add_f32 v[18:19], v[14:15], v[18:19]
	v_pk_add_f32 v[16:17], v[12:13], v[16:17]
	ds_read_b128 v[12:15], v11 offset:8192
	v_lshlrev_b32_e32 v0, 1, v0
	v_lshl_add_u64 v[6:7], v[6:7], 0, v[0:1]
	s_waitcnt lgkmcnt(0)
	v_pk_add_f32 v[18:19], v[18:19], v[14:15]
	v_pk_add_f32 v[16:17], v[16:17], v[12:13]
	ds_read_b128 v[12:15], v11 offset:12288
	s_waitcnt lgkmcnt(0)
	v_pk_add_f32 v[18:19], v[18:19], v[14:15]
	v_pk_add_f32 v[16:17], v[16:17], v[12:13]
	ds_read_b128 v[12:15], v11 offset:16384
	s_waitcnt lgkmcnt(0)
	v_pk_add_f32 v[18:19], v[18:19], v[14:15]
	v_pk_add_f32 v[16:17], v[16:17], v[12:13]
	ds_read_b128 v[12:15], v11 offset:20480
	s_waitcnt lgkmcnt(0)
	v_pk_add_f32 v[18:19], v[18:19], v[14:15]
	v_pk_add_f32 v[16:17], v[16:17], v[12:13]
	ds_read_b128 v[12:15], v11 offset:24576
	s_waitcnt lgkmcnt(0)
	v_pk_add_f32 v[18:19], v[18:19], v[14:15]
	v_pk_add_f32 v[16:17], v[16:17], v[12:13]
	ds_read_b128 v[12:15], v11 offset:28672
	s_waitcnt lgkmcnt(0)
	v_pk_add_f32 v[12:13], v[16:17], v[12:13]
	global_load_dwordx2 v[16:17], v[6:7], off
	v_pk_add_f32 v[14:15], v[18:19], v[14:15]
	s_waitcnt vmcnt(0)
	v_lshlrev_b32_e32 v18, 16, v16
	v_and_b32_e32 v19, 0xffff0000, v16
	v_lshlrev_b32_e32 v16, 16, v17
	v_and_b32_e32 v17, 0xffff0000, v17
	v_pk_add_f32 v[14:15], v[14:15], v[16:17]
	v_pk_add_f32 v[12:13], v[12:13], v[18:19]
	s_nop 0
	v_cvt_pk_bf16_f32 v16, v12, v13
	v_cvt_pk_bf16_f32 v17, v14, v15
	global_store_dwordx2 v[6:7], v[16:17], off
	v_mul_f32_e32 v0, v13, v13
	v_mul_f32_e32 v6, v15, v15
	v_fmac_f32_e32 v0, v12, v12
	v_fmac_f32_e32 v6, v14, v14
	v_add_f32_e32 v0, v0, v6
	ds_bpermute_b32 v6, v112, v0
	s_waitcnt lgkmcnt(0)
	v_add_f32_e32 v0, v0, v6
	ds_bpermute_b32 v6, v113, v0
	s_and_saveexec_b64 s[46:47], s[30:31]
	s_cbranch_execz .LBB0_804
	s_waitcnt lgkmcnt(0)
	v_add_f32_e32 v0, v0, v6
	ds_write_b32 v9, v0 offset:32768

; template <class SEpi>
; __device__ __forceinline__ void sample_gemm(LAS unsigned char* lds, const bf16_t* A, const bf16_t* Bt, int K, const SEpi& E, int wave, int lane) {
;     ...
;         for (int k0 = 0; k0 < nks; k0 += 4) {
;             bf16x8 af[4], bf[4][4];
; #pragma unroll
;             for (int u = 0; u < 4; ++u) { const int ks = (k0 + u < nks) ? k0 + u : k0;
;                 af[u] = *(const bf16x8*)(ap + 32 * ks);
; #pragma unroll
;                 for (int c = 0; c < 4; ++c) bf[u][c] = *(const bf16x8*)(bp + (size_t)(16 * c) * K + 32 * ks); }
; #pragma unroll
;             for (int u = 0; u < 4; ++u) if (k0 + u < nks) {
; #pragma unroll
;                 for (int c = 0; c < 4; ++c) acc[c] = __builtin_amdgcn_mfma_f32_16x16x32_bf16(bf[u][c], af[u], acc[c], 0, 0, 0); }
;         }
.LBB0_1039:
	v_lshl_add_u64 v[28:29], v[24:25], 0, s[48:49]
	v_lshl_add_u64 v[26:27], v[22:23], 0, s[48:49]
	s_mov_b32 s6, 0x3180000
	v_add_co_u32_e32 v64, vcc, s6, v28
	s_nop 1
	v_addc_co_u32_e32 v65, vcc, 0, v29, vcc
	s_mov_b32 s6, 0x3196000
	v_add_co_u32_e32 v70, vcc, s6, v28
	s_nop 1
	v_addc_co_u32_e32 v71, vcc, 0, v29, vcc
	s_mov_b32 s6, 0x31ac000
	v_add_co_u32_e32 v234, vcc, s6, v28
	s_nop 1
	v_addc_co_u32_e32 v235, vcc, 0, v29, vcc
	s_mov_b32 s6, 0x31c2000
	v_add_co_u32_e32 v236, vcc, s6, v28
	s_nop 1
	v_addc_co_u32_e32 v237, vcc, 0, v29, vcc
	global_load_dwordx4 v[34:37], v[26:27], off offset:-128
	global_load_dwordx4 v[38:41], v[64:65], off
	global_load_dwordx4 v[42:45], v[70:71], off
	global_load_dwordx4 v[46:49], v[234:235], off
	global_load_dwordx4 v[50:53], v[236:237], off
	global_load_dwordx4 v[54:57], v[26:27], off offset:-64
	global_load_dwordx4 v[96:99], v[64:65], off offset:64
	global_load_dwordx4 v[100:103], v[70:71], off offset:64
	global_load_dwordx4 v[104:107], v[234:235], off offset:64
	global_load_dwordx4 v[108:111], v[236:237], off offset:64
	global_load_dwordx4 v[166:169], v[26:27], off
	global_load_dwordx4 v[170:173], v[64:65], off offset:128
	global_load_dwordx4 v[174:177], v[70:71], off offset:128
	global_load_dwordx4 v[178:181], v[234:235], off offset:128
	global_load_dwordx4 v[182:185], v[236:237], off offset:128
	global_load_dwordx4 v[186:189], v[26:27], off offset:64
	global_load_dwordx4 v[196:199], v[64:65], off offset:192
	global_load_dwordx4 v[200:203], v[70:71], off offset:192
	global_load_dwordx4 v[206:209], v[234:235], off offset:192
	global_load_dwordx4 v[210:213], v[236:237], off offset:192
	global_load_dwordx4 v[214:217], v[26:27], off offset:128
	global_load_dwordx4 v[218:221], v[64:65], off offset:256
	global_load_dwordx4 v[222:225], v[70:71], off offset:256
	global_load_dwordx4 v[226:229], v[234:235], off offset:256
	global_load_dwordx4 v[230:233], v[236:237], off offset:256
	s_waitcnt vmcnt(20)
	v_mfma_f32_16x16x32_bf16 v[0:3], v[38:41], v[34:37], v[0:3]
	v_mfma_f32_16x16x32_bf16 v[4:7], v[42:45], v[34:37], v[4:7]
	v_mfma_f32_16x16x32_bf16 v[8:11], v[46:49], v[34:37], v[8:11]
	v_mfma_f32_16x16x32_bf16 v[12:15], v[50:53], v[34:37], v[12:15]
	global_load_dwordx4 v[34:37], v[26:27], off offset:192
	global_load_dwordx4 v[38:41], v[64:65], off offset:320
	global_load_dwordx4 v[42:45], v[70:71], off offset:320
	global_load_dwordx4 v[46:49], v[234:235], off offset:320
	global_load_dwordx4 v[50:53], v[236:237], off offset:320
	s_waitcnt vmcnt(20)
	v_mfma_f32_16x16x32_bf16 v[0:3], v[96:99], v[54:57], v[0:3]
	v_mfma_f32_16x16x32_bf16 v[4:7], v[100:103], v[54:57], v[4:7]
	v_mfma_f32_16x16x32_bf16 v[8:11], v[104:107], v[54:57], v[8:11]
	v_mfma_f32_16x16x32_bf16 v[12:15], v[108:111], v[54:57], v[12:15]
	global_load_dwordx4 v[54:57], v[26:27], off offset:256
	global_load_dwordx4 v[96:99], v[64:65], off offset:384
	global_load_dwordx4 v[100:103], v[70:71], off offset:384
	global_load_dwordx4 v[104:107], v[234:235], off offset:384
	global_load_dwordx4 v[108:111], v[236:237], off offset:384
	s_waitcnt vmcnt(20)
	v_mfma_f32_16x16x32_bf16 v[0:3], v[170:173], v[166:169], v[0:3]
	v_mfma_f32_16x16x32_bf16 v[4:7], v[174:177], v[166:169], v[4:7]
	v_mfma_f32_16x16x32_bf16 v[8:11], v[178:181], v[166:169], v[8:11]
	v_mfma_f32_16x16x32_bf16 v[12:15], v[182:185], v[166:169], v[12:15]
	global_load_dwordx4 v[166:169], v[26:27], off offset:320
	global_load_dwordx4 v[170:173], v[64:65], off offset:448
	global_load_dwordx4 v[174:177], v[70:71], off offset:448
	global_load_dwordx4 v[178:181], v[234:235], off offset:448
	global_load_dwordx4 v[182:185], v[236:237], off offset:448
	s_waitcnt vmcnt(20)
	v_mfma_f32_16x16x32_bf16 v[0:3], v[196:199], v[186:189], v[0:3]
	v_mfma_f32_16x16x32_bf16 v[4:7], v[200:203], v[186:189], v[4:7]
	v_mfma_f32_16x16x32_bf16 v[8:11], v[206:209], v[186:189], v[8:11]
	v_mfma_f32_16x16x32_bf16 v[12:15], v[210:213], v[186:189], v[12:15]
	global_load_dwordx4 v[186:189], v[26:27], off offset:384
	global_load_dwordx4 v[196:199], v[64:65], off offset:512
	global_load_dwordx4 v[200:203], v[70:71], off offset:512
	global_load_dwordx4 v[206:209], v[234:235], off offset:512
	global_load_dwordx4 v[210:213], v[236:237], off offset:512
	s_waitcnt vmcnt(20)
	v_mfma_f32_16x16x32_bf16 v[0:3], v[218:221], v[214:217], v[0:3]
	v_mfma_f32_16x16x32_bf16 v[4:7], v[222:225], v[214:217], v[4:7]
	v_mfma_f32_16x16x32_bf16 v[8:11], v[226:229], v[214:217], v[8:11]
	v_mfma_f32_16x16x32_bf16 v[12:15], v[230:233], v[214:217], v[12:15]
	global_load_dwordx4 v[214:217], v[26:27], off offset:448
	global_load_dwordx4 v[218:221], v[64:65], off offset:576
	global_load_dwordx4 v[222:225], v[70:71], off offset:576
	global_load_dwordx4 v[226:229], v[234:235], off offset:576
	global_load_dwordx4 v[230:233], v[236:237], off offset:576
	s_waitcnt vmcnt(20)
	v_mfma_f32_16x16x32_bf16 v[0:3], v[38:41], v[34:37], v[0:3]
	v_mfma_f32_16x16x32_bf16 v[4:7], v[42:45], v[34:37], v[4:7]
	v_mfma_f32_16x16x32_bf16 v[8:11], v[46:49], v[34:37], v[8:11]
	v_mfma_f32_16x16x32_bf16 v[12:15], v[50:53], v[34:37], v[12:15]
	global_load_dwordx4 v[34:37], v[26:27], off offset:512
	global_load_dwordx4 v[38:41], v[64:65], off offset:640
	global_load_dwordx4 v[42:45], v[70:71], off offset:640
	global_load_dwordx4 v[46:49], v[234:235], off offset:640
	global_load_dwordx4 v[50:53], v[236:237], off offset:640
	s_waitcnt vmcnt(20)
	v_mfma_f32_16x16x32_bf16 v[0:3], v[96:99], v[54:57], v[0:3]
	v_mfma_f32_16x16x32_bf16 v[4:7], v[100:103], v[54:57], v[4:7]
	v_mfma_f32_16x16x32_bf16 v[8:11], v[104:107], v[54:57], v[8:11]
	v_mfma_f32_16x16x32_bf16 v[12:15], v[108:111], v[54:57], v[12:15]
	s_waitcnt vmcnt(15)
	v_mfma_f32_16x16x32_bf16 v[0:3], v[170:173], v[166:169], v[0:3]
	v_mfma_f32_16x16x32_bf16 v[4:7], v[174:177], v[166:169], v[4:7]
	v_mfma_f32_16x16x32_bf16 v[8:11], v[178:181], v[166:169], v[8:11]
	v_mfma_f32_16x16x32_bf16 v[12:15], v[182:185], v[166:169], v[12:15]
	s_waitcnt vmcnt(10)
	v_mfma_f32_16x16x32_bf16 v[0:3], v[196:199], v[186:189], v[0:3]
	v_mfma_f32_16x16x32_bf16 v[4:7], v[200:203], v[186:189], v[4:7]
	v_mfma_f32_16x16x32_bf16 v[8:11], v[206:209], v[186:189], v[8:11]
	v_mfma_f32_16x16x32_bf16 v[12:15], v[210:213], v[186:189], v[12:15]
	s_waitcnt vmcnt(5)
	v_mfma_f32_16x16x32_bf16 v[0:3], v[218:221], v[214:217], v[0:3]
	v_mfma_f32_16x16x32_bf16 v[4:7], v[222:225], v[214:217], v[4:7]
	v_mfma_f32_16x16x32_bf16 v[8:11], v[226:229], v[214:217], v[8:11]
	v_mfma_f32_16x16x32_bf16 v[12:15], v[230:233], v[214:217], v[12:15]
	s_waitcnt vmcnt(0)
	v_mfma_f32_16x16x32_bf16 v[0:3], v[38:41], v[34:37], v[0:3]
	v_mfma_f32_16x16x32_bf16 v[4:7], v[42:45], v[34:37], v[4:7]
	v_mfma_f32_16x16x32_bf16 v[8:11], v[46:49], v[34:37], v[8:11]
	v_mfma_f32_16x16x32_bf16 v[12:15], v[50:53], v[34:37], v[12:15]

; template <class SEpi>
; __device__ __forceinline__ void sample_gemm(LAS unsigned char* lds, const bf16_t* A, const bf16_t* Bt, int K, const SEpi& E, int wave, int lane) {
;     ...
;         for (int k0 = 0; k0 < nks; k0 += 4) {
;             bf16x8 af[4], bf[4][4];
; #pragma unroll
;             for (int u = 0; u < 4; ++u) { const int ks = (k0 + u < nks) ? k0 + u : k0;
;                 af[u] = *(const bf16x8*)(ap + 32 * ks);
; #pragma unroll
;                 for (int c = 0; c < 4; ++c) bf[u][c] = *(const bf16x8*)(bp + (size_t)(16 * c) * K + 32 * ks); }
; #pragma unroll
;             for (int u = 0; u < 4; ++u) if (k0 + u < nks) {
; #pragma unroll
;                 for (int c = 0; c < 4; ++c) acc[c] = __builtin_amdgcn_mfma_f32_16x16x32_bf16(bf[u][c], af[u], acc[c], 0, 0, 0); }
;         }
.LBB0_1281:
	v_lshl_add_u64 v[28:29], v[24:25], 0, s[48:49]
	v_lshl_add_u64 v[26:27], v[22:23], 0, s[48:49]
	s_mov_b32 s6, 0x3700000
	v_add_co_u32_e32 v64, vcc, s6, v28
	s_nop 1
	v_addc_co_u32_e32 v65, vcc, 0, v29, vcc
	s_mov_b32 s6, 0x3716000
	v_add_co_u32_e32 v70, vcc, s6, v28
	s_nop 1
	v_addc_co_u32_e32 v71, vcc, 0, v29, vcc
	s_mov_b32 s6, 0x372c000
	v_add_co_u32_e32 v234, vcc, s6, v28
	s_nop 1
	v_addc_co_u32_e32 v235, vcc, 0, v29, vcc
	s_mov_b32 s6, 0x3742000
	v_add_co_u32_e32 v236, vcc, s6, v28
	s_nop 1
	v_addc_co_u32_e32 v237, vcc, 0, v29, vcc
	global_load_dwordx4 v[34:37], v[26:27], off offset:-128
	global_load_dwordx4 v[38:41], v[64:65], off
	global_load_dwordx4 v[42:45], v[70:71], off
	global_load_dwordx4 v[46:49], v[234:235], off
	global_load_dwordx4 v[50:53], v[236:237], off
	global_load_dwordx4 v[54:57], v[26:27], off offset:-64
	global_load_dwordx4 v[96:99], v[64:65], off offset:64
	global_load_dwordx4 v[100:103], v[70:71], off offset:64
	global_load_dwordx4 v[104:107], v[234:235], off offset:64
	global_load_dwordx4 v[108:111], v[236:237], off offset:64
	global_load_dwordx4 v[166:169], v[26:27], off
	global_load_dwordx4 v[170:173], v[64:65], off offset:128
	global_load_dwordx4 v[174:177], v[70:71], off offset:128
	global_load_dwordx4 v[178:181], v[234:235], off offset:128
	global_load_dwordx4 v[182:185], v[236:237], off offset:128
	global_load_dwordx4 v[186:189], v[26:27], off offset:64
	global_load_dwordx4 v[196:199], v[64:65], off offset:192
	global_load_dwordx4 v[200:203], v[70:71], off offset:192
	global_load_dwordx4 v[206:209], v[234:235], off offset:192
	global_load_dwordx4 v[210:213], v[236:237], off offset:192
	global_load_dwordx4 v[214:217], v[26:27], off offset:128
	global_load_dwordx4 v[218:221], v[64:65], off offset:256
	global_load_dwordx4 v[222:225], v[70:71], off offset:256
	global_load_dwordx4 v[226:229], v[234:235], off offset:256
	global_load_dwordx4 v[230:233], v[236:237], off offset:256
	s_waitcnt vmcnt(20)
	v_mfma_f32_16x16x32_bf16 v[0:3], v[38:41], v[34:37], v[0:3]
	v_mfma_f32_16x16x32_bf16 v[4:7], v[42:45], v[34:37], v[4:7]
	v_mfma_f32_16x16x32_bf16 v[8:11], v[46:49], v[34:37], v[8:11]
	v_mfma_f32_16x16x32_bf16 v[12:15], v[50:53], v[34:37], v[12:15]
	global_load_dwordx4 v[34:37], v[26:27], off offset:192
	global_load_dwordx4 v[38:41], v[64:65], off offset:320
	global_load_dwordx4 v[42:45], v[70:71], off offset:320
	global_load_dwordx4 v[46:49], v[234:235], off offset:320
	global_load_dwordx4 v[50:53], v[236:237], off offset:320
	s_waitcnt vmcnt(20)
	v_mfma_f32_16x16x32_bf16 v[0:3], v[96:99], v[54:57], v[0:3]
	v_mfma_f32_16x16x32_bf16 v[4:7], v[100:103], v[54:57], v[4:7]
	v_mfma_f32_16x16x32_bf16 v[8:11], v[104:107], v[54:57], v[8:11]
	v_mfma_f32_16x16x32_bf16 v[12:15], v[108:111], v[54:57], v[12:15]
	global_load_dwordx4 v[54:57], v[26:27], off offset:256
	global_load_dwordx4 v[96:99], v[64:65], off offset:384
	global_load_dwordx4 v[100:103], v[70:71], off offset:384
	global_load_dwordx4 v[104:107], v[234:235], off offset:384
	global_load_dwordx4 v[108:111], v[236:237], off offset:384
	s_waitcnt vmcnt(20)
	v_mfma_f32_16x16x32_bf16 v[0:3], v[170:173], v[166:169], v[0:3]
	v_mfma_f32_16x16x32_bf16 v[4:7], v[174:177], v[166:169], v[4:7]
	v_mfma_f32_16x16x32_bf16 v[8:11], v[178:181], v[166:169], v[8:11]
	v_mfma_f32_16x16x32_bf16 v[12:15], v[182:185], v[166:169], v[12:15]
	global_load_dwordx4 v[166:169], v[26:27], off offset:320
	global_load_dwordx4 v[170:173], v[64:65], off offset:448
	global_load_dwordx4 v[174:177], v[70:71], off offset:448
	global_load_dwordx4 v[178:181], v[234:235], off offset:448
	global_load_dwordx4 v[182:185], v[236:237], off offset:448
	s_waitcnt vmcnt(20)
	v_mfma_f32_16x16x32_bf16 v[0:3], v[196:199], v[186:189], v[0:3]
	v_mfma_f32_16x16x32_bf16 v[4:7], v[200:203], v[186:189], v[4:7]
	v_mfma_f32_16x16x32_bf16 v[8:11], v[206:209], v[186:189], v[8:11]
	v_mfma_f32_16x16x32_bf16 v[12:15], v[210:213], v[186:189], v[12:15]
	global_load_dwordx4 v[186:189], v[26:27], off offset:384
	global_load_dwordx4 v[196:199], v[64:65], off offset:512
	global_load_dwordx4 v[200:203], v[70:71], off offset:512
	global_load_dwordx4 v[206:209], v[234:235], off offset:512
	global_load_dwordx4 v[210:213], v[236:237], off offset:512
	s_waitcnt vmcnt(20)
	v_mfma_f32_16x16x32_bf16 v[0:3], v[218:221], v[214:217], v[0:3]
	v_mfma_f32_16x16x32_bf16 v[4:7], v[222:225], v[214:217], v[4:7]
	v_mfma_f32_16x16x32_bf16 v[8:11], v[226:229], v[214:217], v[8:11]
	v_mfma_f32_16x16x32_bf16 v[12:15], v[230:233], v[214:217], v[12:15]
	global_load_dwordx4 v[214:217], v[26:27], off offset:448
	global_load_dwordx4 v[218:221], v[64:65], off offset:576
	global_load_dwordx4 v[222:225], v[70:71], off offset:576
	global_load_dwordx4 v[226:229], v[234:235], off offset:576
	global_load_dwordx4 v[230:233], v[236:237], off offset:576
	s_waitcnt vmcnt(20)
	v_mfma_f32_16x16x32_bf16 v[0:3], v[38:41], v[34:37], v[0:3]
	v_mfma_f32_16x16x32_bf16 v[4:7], v[42:45], v[34:37], v[4:7]
	v_mfma_f32_16x16x32_bf16 v[8:11], v[46:49], v[34:37], v[8:11]
	v_mfma_f32_16x16x32_bf16 v[12:15], v[50:53], v[34:37], v[12:15]
	global_load_dwordx4 v[34:37], v[26:27], off offset:512
	global_load_dwordx4 v[38:41], v[64:65], off offset:640
	global_load_dwordx4 v[42:45], v[70:71], off offset:640
	global_load_dwordx4 v[46:49], v[234:235], off offset:640
	global_load_dwordx4 v[50:53], v[236:237], off offset:640
	s_waitcnt vmcnt(20)
	v_mfma_f32_16x16x32_bf16 v[0:3], v[96:99], v[54:57], v[0:3]
	v_mfma_f32_16x16x32_bf16 v[4:7], v[100:103], v[54:57], v[4:7]
	v_mfma_f32_16x16x32_bf16 v[8:11], v[104:107], v[54:57], v[8:11]
	v_mfma_f32_16x16x32_bf16 v[12:15], v[108:111], v[54:57], v[12:15]
	s_waitcnt vmcnt(15)
	v_mfma_f32_16x16x32_bf16 v[0:3], v[170:173], v[166:169], v[0:3]
	v_mfma_f32_16x16x32_bf16 v[4:7], v[174:177], v[166:169], v[4:7]
	v_mfma_f32_16x16x32_bf16 v[8:11], v[178:181], v[166:169], v[8:11]
	v_mfma_f32_16x16x32_bf16 v[12:15], v[182:185], v[166:169], v[12:15]
	s_waitcnt vmcnt(10)
	v_mfma_f32_16x16x32_bf16 v[0:3], v[196:199], v[186:189], v[0:3]
	v_mfma_f32_16x16x32_bf16 v[4:7], v[200:203], v[186:189], v[4:7]
	v_mfma_f32_16x16x32_bf16 v[8:11], v[206:209], v[186:189], v[8:11]
	v_mfma_f32_16x16x32_bf16 v[12:15], v[210:213], v[186:189], v[12:15]
	s_waitcnt vmcnt(5)
	v_mfma_f32_16x16x32_bf16 v[0:3], v[218:221], v[214:217], v[0:3]
	v_mfma_f32_16x16x32_bf16 v[4:7], v[222:225], v[214:217], v[4:7]
	v_mfma_f32_16x16x32_bf16 v[8:11], v[226:229], v[214:217], v[8:11]
	v_mfma_f32_16x16x32_bf16 v[12:15], v[230:233], v[214:217], v[12:15]
	s_waitcnt vmcnt(0)
	v_mfma_f32_16x16x32_bf16 v[0:3], v[38:41], v[34:37], v[0:3]
	v_mfma_f32_16x16x32_bf16 v[4:7], v[42:45], v[34:37], v[4:7]
	v_mfma_f32_16x16x32_bf16 v[8:11], v[46:49], v[34:37], v[8:11]
	v_mfma_f32_16x16x32_bf16 v[12:15], v[50:53], v[34:37], v[12:15]

;     __device__ __forceinline__ float apply(const f32x4 acc, int row, int col, int fq) const {
;         const f32x4 p = *(const f32x4*)(ssq + (size_t)row * 16 + 4 * fq); float t = (p[0] + p[1]) + (p[2] + p[3]); t += __shfl_xor(t, 16); t += __shfl_xor(t, 32);
;         const float sc = rsqrtf(t * (1.0f / D) + NORM_EPS);
;         *(f32x4*)(ubuf + (size_t)row * D + col) = acc * sc; return 0.f;
;     }
; template <class SEpi>
; __device__ __forceinline__ void sample_gemm(LAS unsigned char* lds, const bf16_t* A, const bf16_t* Bt, int K, const SEpi& E, int wave, int lane) {
;     ...
;         const int rt = piece >> 4, cg = piece & 15, row = MP + 16 * rt + fr;
;         const bf16_t* ap = A + (size_t)row * K + wave * (K >> 3) + 8 * fq; const bf16_t* bp = Bt + (size_t)(64 * cg + fr) * K + wave * (K >> 3) + 8 * fq;
;         f32x4 acc[4];
; #pragma unroll
;         for (int c = 0; c < 4; ++c) acc[c] = (f32x4){0.f, 0.f, 0.f, 0.f};
; #pragma unroll 1
;         for (int k0 = 0; k0 < nks; k0 += 4) {
;             bf16x8 af[4], bf[4][4];
; #pragma unroll
;             for (int u = 0; u < 4; ++u) { const int ks = (k0 + u < nks) ? k0 + u : k0;
;                 af[u] = *(const bf16x8*)(ap + 32 * ks);
; #pragma unroll
;                 for (int c = 0; c < 4; ++c) bf[u][c] = *(const bf16x8*)(bp + (size_t)(16 * c) * K + 32 * ks); }
; #pragma unroll
;             for (int u = 0; u < 4; ++u) if (k0 + u < nks) {
; #pragma unroll
;                 for (int c = 0; c < 4; ++c) acc[c] = __builtin_amdgcn_mfma_f32_16x16x32_bf16(bf[u][c], af[u], acc[c], 0, 0, 0); }
;         }
;         asm volatile("s_nop 15\n\ts_nop 15" : "+v"(acc[0]), "+v"(acc[1]), "+v"(acc[2]), "+v"(acc[3]));
; #pragma unroll
;         for (int c = 0; c < 4; ++c) red[(wave * 4 + c) * 64 + lane] = acc[c];
;         __syncthreads();
;         if (wave < 4) {
;             f32x4 t = red[wave * 64 + lane];
; #pragma unroll
;             for (int w = 1; w < 8; ++w) t += red[(w * 4 + wave) * 64 + lane];
;             float q = E.apply(t, row, 64 * cg + 16 * wave + 4 * fq, fq);
;             if (SEpi::HAS_SSQ) { q += __shfl_xor(q, 16); q += __shfl_xor(q, 32); if (fq == 0) P[wave * 16 + fr] = q; }
;         }
;         __syncthreads();
;         if (SEpi::HAS_SSQ && wave == 0 && lane < 16) E.ssq_out[(size_t)(MP + 16 * rt + lane) * 16 + cg] = (P[lane] + P[16 + lane]) + (P[32 + lane] + P[48 + lane]);
;         __syncthreads();
.LBB0_1402:
	s_and_b32 s29, s26, 0x3c0
	v_or_b32_e32 v0, s29, v161
	v_lshlrev_b32_e32 v0, 11, v0
	v_lshl_add_u64 v[46:47], v[4:5], 0, v[0:1]
	v_add_co_u32_e32 v50, vcc, 0x8000, v46
	s_and_b32 s6, s28, -16
	s_nop 0
	v_addc_co_u32_e32 v51, vcc, 0, v47, vcc
	v_add_u32_e32 v8, s6, v163
	global_load_dwordx4 v[96:99], v[46:47], off
	v_add_co_u32_e32 v52, vcc, 0x10000, v46
	v_ashrrev_i32_e32 v9, 31, v8
	s_nop 0
	v_addc_co_u32_e32 v53, vcc, 0, v47, vcc
	v_lshlrev_b64 v[18:19], 11, v[8:9]
	v_add_co_u32_e32 v54, vcc, 0x18000, v46
	v_lshl_add_u64 v[48:49], v[2:3], 0, v[18:19]
	s_nop 0
	v_addc_co_u32_e32 v55, vcc, 0, v47, vcc
	global_load_dwordx4 v[100:103], v[48:49], off
	global_load_dwordx4 v[104:107], v[50:51], off
	global_load_dwordx4 v[108:111], v[52:53], off
	global_load_dwordx4 v[172:175], v[46:47], off offset:64
	global_load_dwordx4 v[176:179], v[54:55], off
	global_load_dwordx4 v[180:183], v[48:49], off offset:64
	s_and_b64 vcc, exec, s[46:47]
	global_load_dwordx4 v[184:187], v[52:53], off offset:64
	global_load_dwordx4 v[198:201], v[50:51], off offset:64
	global_load_dwordx4 v[206:209], v[46:47], off offset:128
	global_load_dwordx4 v[210:213], v[48:49], off offset:128
	global_load_dwordx4 v[214:217], v[54:55], off offset:64
	global_load_dwordx4 v[218:221], v[50:51], off offset:128
	global_load_dwordx4 v[222:225], v[52:53], off offset:128
	global_load_dwordx4 v[226:229], v[46:47], off offset:192
	global_load_dwordx4 v[230:233], v[48:49], off offset:192
	global_load_dwordx4 v[234:237], v[54:55], off offset:128
	global_load_dwordx4 v[238:241], v[50:51], off offset:192
	global_load_dwordx4 v[244:247], v[52:53], off offset:192
	global_load_dwordx4 v[248:251], v[54:55], off offset:192
	s_waitcnt vmcnt(0)
	v_mfma_f32_16x16x32_bf16 v[26:29], v[108:111], v[100:103], 0
	v_mfma_f32_16x16x32_bf16 v[14:17], v[96:99], v[100:103], 0
	v_mfma_f32_16x16x32_bf16 v[22:25], v[104:107], v[100:103], 0
	v_mfma_f32_16x16x32_bf16 v[18:21], v[176:179], v[100:103], 0
	v_mfma_f32_16x16x32_bf16 v[14:17], v[172:175], v[180:183], v[14:17]
	v_mfma_f32_16x16x32_bf16 v[22:25], v[198:201], v[180:183], v[22:25]
	v_mfma_f32_16x16x32_bf16 v[26:29], v[184:187], v[180:183], v[26:29]
	v_mfma_f32_16x16x32_bf16 v[14:17], v[206:209], v[210:213], v[14:17]
	v_mfma_f32_16x16x32_bf16 v[18:21], v[214:217], v[180:183], v[18:21]
	v_mfma_f32_16x16x32_bf16 v[22:25], v[218:221], v[210:213], v[22:25]
	v_mfma_f32_16x16x32_bf16 v[26:29], v[222:225], v[210:213], v[26:29]
	v_mfma_f32_16x16x32_bf16 v[14:17], v[226:229], v[230:233], v[14:17]
	v_mfma_f32_16x16x32_bf16 v[18:21], v[234:237], v[210:213], v[18:21]
	v_mfma_f32_16x16x32_bf16 v[22:25], v[238:241], v[230:233], v[22:25]
	v_mfma_f32_16x16x32_bf16 v[26:29], v[244:247], v[230:233], v[26:29]
	v_mfma_f32_16x16x32_bf16 v[18:21], v[248:251], v[230:233], v[18:21]
	s_nop 7
	ds_write_b128 v10, v[14:17]
	s_nop 0
	ds_write_b128 v10, v[22:25] offset:1024
	s_nop 1
	ds_write_b128 v10, v[26:29] offset:2048
	s_nop 1
	ds_write_b128 v10, v[18:21] offset:3072
	s_waitcnt lgkmcnt(0)
	s_barrier
	s_cbranch_vccnz .LBB0_1401
	v_add_u32_e32 v0, s4, v197
	ds_read_b128 v[14:17], v0
	ds_read_b128 v[18:21], v0 offset:4096
	s_mov_b32 s6, 0x800000
	v_or_b32_e32 v13, s29, v196
	s_waitcnt lgkmcnt(0)
	v_pk_add_f32 v[20:21], v[16:17], v[20:21]
	v_pk_add_f32 v[18:19], v[14:15], v[18:19]
	ds_read_b128 v[14:17], v0 offset:8192
	s_waitcnt lgkmcnt(0)
	v_pk_add_f32 v[20:21], v[20:21], v[16:17]
	v_pk_add_f32 v[18:19], v[18:19], v[14:15]
	ds_read_b128 v[14:17], v0 offset:12288
	s_waitcnt lgkmcnt(0)
	v_pk_add_f32 v[20:21], v[20:21], v[16:17]
	v_pk_add_f32 v[18:19], v[18:19], v[14:15]
	ds_read_b128 v[14:17], v0 offset:16384
	s_waitcnt lgkmcnt(0)
	v_pk_add_f32 v[20:21], v[20:21], v[16:17]
	v_pk_add_f32 v[18:19], v[18:19], v[14:15]
	ds_read_b128 v[14:17], v0 offset:20480
	s_waitcnt lgkmcnt(0)
	v_pk_add_f32 v[20:21], v[20:21], v[16:17]
	v_pk_add_f32 v[18:19], v[18:19], v[14:15]
	ds_read_b128 v[14:17], v0 offset:24576
	s_waitcnt lgkmcnt(0)
	v_pk_add_f32 v[20:21], v[20:21], v[16:17]
	v_pk_add_f32 v[18:19], v[18:19], v[14:15]
	ds_read_b128 v[14:17], v0 offset:28672
	s_waitcnt lgkmcnt(0)
	v_pk_add_f32 v[18:19], v[18:19], v[14:15]
	v_lshlrev_b64 v[14:15], 6, v[8:9]
	v_lshl_add_u64 v[14:15], v[6:7], 0, v[14:15]
	v_pk_add_f32 v[20:21], v[20:21], v[16:17]
	global_load_dwordx4 v[14:17], v[14:15], off
	v_lshlrev_b64 v[8:9], 12, v[8:9]
	v_lshl_add_u64 v[8:9], s[24:25], 0, v[8:9]
	s_waitcnt vmcnt(0)
	v_mov_b32_e32 v22, v15
	v_mov_b32_e32 v23, v16
	v_mov_b32_e32 v15, v17
	v_pk_add_f32 v[14:15], v[22:23], v[14:15]
	s_nop 0
	v_add_f32_e32 v0, v14, v15
	v_and_b32_e32 v15, 64, v12
	v_xor_b32_e32 v14, 16, v12
	v_add_u32_e32 v15, 64, v15
	v_cmp_lt_i32_e32 vcc, v14, v15
	s_nop 1
	v_cndmask_b32_e32 v14, v12, v14, vcc
	v_lshlrev_b32_e32 v14, 2, v14
	ds_bpermute_b32 v14, v14, v0
	s_waitcnt lgkmcnt(0)
	v_add_f32_e32 v0, v0, v14
	v_xor_b32_e32 v14, 32, v12
	v_cmp_lt_i32_e32 vcc, v14, v15
	s_nop 1
	v_cndmask_b32_e32 v14, v12, v14, vcc
	v_lshlrev_b32_e32 v14, 2, v14
	ds_bpermute_b32 v14, v14, v0
	s_waitcnt lgkmcnt(0)
	v_add_f32_e32 v0, v0, v14
	v_fmamk_f32 v0, v0, 0x3a800000, v11
	v_cmp_gt_f32_e32 vcc, s6, v0
	v_mul_f32_e32 v14, 0x4b800000, v0
	s_nop 0
	v_cndmask_b32_e32 v0, v0, v14, vcc
	v_rsq_f32_e32 v0, v0
	s_nop 0
	v_mul_f32_e32 v14, 0x45800000, v0
	v_cndmask_b32_e32 v0, v0, v14, vcc
	v_pk_mul_f32 v[16:17], v[20:21], v[0:1] op_sel_hi:[1,0]
	v_pk_mul_f32 v[14:15], v[18:19], v[0:1] op_sel_hi:[1,0]
	v_lshlrev_b32_e32 v0, 2, v13
	v_lshl_add_u64 v[8:9], v[8:9], 0, v[0:1]
	global_store_dwordx4 v[8:9], v[14:17], off
	s_branch .LBB0_1401

;     __device__ __forceinline__ float apply(const f32x4 acc, int row, int col, int fq) const {
;         const u32x2 g4 = *(const u32x2*)(gbuf + (size_t)row * D + col); const f32x4 av = acc + *(const f32x4*)(bglu + col);
;         u32x2 w; w.x = cvt_pk_bf16(__uint_as_float(g4.x << 16) * fast_sigmoid(av[0]), __uint_as_float(g4.x & 0xffff0000u) * fast_sigmoid(av[1]));
; template <class SEpi>
; __device__ __forceinline__ void sample_gemm(LAS unsigned char* lds, const bf16_t* A, const bf16_t* Bt, int K, const SEpi& E, int wave, int lane) {
;     ...
;         const int rt = piece >> 4, cg = piece & 15, row = MP + 16 * rt + fr;
;         const bf16_t* ap = A + (size_t)row * K + wave * (K >> 3) + 8 * fq; const bf16_t* bp = Bt + (size_t)(64 * cg + fr) * K + wave * (K >> 3) + 8 * fq;
;         f32x4 acc[4];
; #pragma unroll
;         for (int c = 0; c < 4; ++c) acc[c] = (f32x4){0.f, 0.f, 0.f, 0.f};
; #pragma unroll 1
;         for (int k0 = 0; k0 < nks; k0 += 4) {
;             bf16x8 af[4], bf[4][4];
; #pragma unroll
;             for (int u = 0; u < 4; ++u) { const int ks = (k0 + u < nks) ? k0 + u : k0;
;                 af[u] = *(const bf16x8*)(ap + 32 * ks);
; #pragma unroll
;                 for (int c = 0; c < 4; ++c) bf[u][c] = *(const bf16x8*)(bp + (size_t)(16 * c) * K + 32 * ks); }
; #pragma unroll
;             for (int u = 0; u < 4; ++u) if (k0 + u < nks) {
; #pragma unroll
;                 for (int c = 0; c < 4; ++c) acc[c] = __builtin_amdgcn_mfma_f32_16x16x32_bf16(bf[u][c], af[u], acc[c], 0, 0, 0); }
;         }
;         asm volatile("s_nop 15\n\ts_nop 15" : "+v"(acc[0]), "+v"(acc[1]), "+v"(acc[2]), "+v"(acc[3]));
; #pragma unroll
;         for (int c = 0; c < 4; ++c) red[(wave * 4 + c) * 64 + lane] = acc[c];
;         __syncthreads();
;         if (wave < 4) {
;             f32x4 t = red[wave * 64 + lane];
; #pragma unroll
;             for (int w = 1; w < 8; ++w) t += red[(w * 4 + wave) * 64 + lane];
;             float q = E.apply(t, row, 64 * cg + 16 * wave + 4 * fq, fq);
;             if (SEpi::HAS_SSQ) { q += __shfl_xor(q, 16); q += __shfl_xor(q, 32); if (fq == 0) P[wave * 16 + fr] = q; }
;         }
;         __syncthreads();
;         if (SEpi::HAS_SSQ && wave == 0 && lane < 16) E.ssq_out[(size_t)(MP + 16 * rt + lane) * 16 + cg] = (P[lane] + P[16 + lane]) + (P[32 + lane] + P[48 + lane]);
;         __syncthreads();
.LBB0_1625:
	s_and_b32 s27, s4, 0x3c0
	v_or_b32_e32 v0, s27, v161
	v_lshlrev_b32_e32 v0, 11, v0
	v_lshl_add_u64 v[8:9], v[4:5], 0, v[0:1]
	v_add_co_u32_e32 v46, vcc, 0x8000, v8
	s_and_b32 s6, s26, -16
	s_nop 0
	v_addc_co_u32_e32 v47, vcc, 0, v9, vcc
	v_add_u32_e32 v6, s6, v163
	global_load_dwordx4 v[68:71], v[8:9], off
	v_add_co_u32_e32 v48, vcc, 0x10000, v8
	v_ashrrev_i32_e32 v7, 31, v6
	s_nop 0
	v_addc_co_u32_e32 v49, vcc, 0, v9, vcc
	v_lshlrev_b64 v[6:7], 11, v[6:7]
	v_add_co_u32_e32 v50, vcc, 0x18000, v8
	v_lshl_add_u64 v[44:45], v[2:3], 0, v[6:7]
	s_nop 0
	v_addc_co_u32_e32 v51, vcc, 0, v9, vcc
	global_load_dwordx4 v[72:75], v[44:45], off
	global_load_dwordx4 v[76:79], v[46:47], off
	global_load_dwordx4 v[80:83], v[48:49], off
	global_load_dwordx4 v[84:87], v[8:9], off offset:64
	global_load_dwordx4 v[88:91], v[50:51], off
	global_load_dwordx4 v[92:95], v[44:45], off offset:64
	s_and_b64 vcc, exec, s[46:47]
	global_load_dwordx4 v[96:99], v[48:49], off offset:64
	global_load_dwordx4 v[100:103], v[46:47], off offset:64
	global_load_dwordx4 v[104:107], v[8:9], off offset:128
	global_load_dwordx4 v[108:111], v[44:45], off offset:128
	global_load_dwordx4 v[112:115], v[50:51], off offset:64
	global_load_dwordx4 v[116:119], v[46:47], off offset:128
	global_load_dwordx4 v[120:123], v[48:49], off offset:128
	global_load_dwordx4 v[124:127], v[8:9], off offset:192
	global_load_dwordx4 v[128:131], v[44:45], off offset:192
	global_load_dwordx4 v[132:135], v[50:51], off offset:128
	global_load_dwordx4 v[136:139], v[46:47], off offset:192
	global_load_dwordx4 v[140:143], v[48:49], off offset:192
	global_load_dwordx4 v[144:147], v[50:51], off offset:192
	s_waitcnt vmcnt(0)
	v_mfma_f32_16x16x32_bf16 v[24:27], v[80:83], v[72:75], 0
	v_mfma_f32_16x16x32_bf16 v[12:15], v[68:71], v[72:75], 0
	v_mfma_f32_16x16x32_bf16 v[20:23], v[76:79], v[72:75], 0
	v_mfma_f32_16x16x32_bf16 v[16:19], v[88:91], v[72:75], 0
	v_mfma_f32_16x16x32_bf16 v[12:15], v[84:87], v[92:95], v[12:15]
	v_mfma_f32_16x16x32_bf16 v[20:23], v[100:103], v[92:95], v[20:23]
	v_mfma_f32_16x16x32_bf16 v[24:27], v[96:99], v[92:95], v[24:27]
	v_mfma_f32_16x16x32_bf16 v[12:15], v[104:107], v[108:111], v[12:15]
	v_mfma_f32_16x16x32_bf16 v[16:19], v[112:115], v[92:95], v[16:19]
	v_mfma_f32_16x16x32_bf16 v[20:23], v[116:119], v[108:111], v[20:23]
	v_mfma_f32_16x16x32_bf16 v[24:27], v[120:123], v[108:111], v[24:27]
	v_mfma_f32_16x16x32_bf16 v[12:15], v[124:127], v[128:131], v[12:15]
	v_mfma_f32_16x16x32_bf16 v[16:19], v[132:135], v[108:111], v[16:19]
	v_mfma_f32_16x16x32_bf16 v[20:23], v[136:139], v[128:131], v[20:23]
	v_mfma_f32_16x16x32_bf16 v[24:27], v[140:143], v[128:131], v[24:27]
	v_mfma_f32_16x16x32_bf16 v[16:19], v[144:147], v[128:131], v[16:19]
	s_nop 7
	ds_write_b128 v10, v[12:15]
	s_nop 0
	ds_write_b128 v10, v[20:23] offset:1024
	s_nop 1
	ds_write_b128 v10, v[24:27] offset:2048
	s_nop 1
	ds_write_b128 v10, v[16:19] offset:3072
	s_waitcnt lgkmcnt(0)
	s_barrier
	s_cbranch_vccnz .LBB0_1624
	ds_read_b128 v[12:15], v11
	ds_read_b128 v[16:19], v11 offset:4096
	s_load_dwordx2 s[6:7], s[0:1], 0xb8
	s_waitcnt lgkmcnt(0)
	v_pk_add_f32 v[8:9], v[14:15], v[18:19]
	v_pk_add_f32 v[16:17], v[12:13], v[16:17]
	ds_read_b128 v[12:15], v11 offset:8192
	s_waitcnt lgkmcnt(0)
	v_pk_add_f32 v[8:9], v[8:9], v[14:15]
	v_pk_add_f32 v[16:17], v[16:17], v[12:13]
	ds_read_b128 v[12:15], v11 offset:12288
	s_waitcnt lgkmcnt(0)
	v_pk_add_f32 v[8:9], v[8:9], v[14:15]
	v_pk_add_f32 v[16:17], v[16:17], v[12:13]
	ds_read_b128 v[12:15], v11 offset:16384
	s_waitcnt lgkmcnt(0)
	v_pk_add_f32 v[8:9], v[8:9], v[14:15]
	v_pk_add_f32 v[16:17], v[16:17], v[12:13]
	ds_read_b128 v[12:15], v11 offset:20480
	s_waitcnt lgkmcnt(0)
	v_pk_add_f32 v[8:9], v[8:9], v[14:15]
	v_pk_add_f32 v[16:17], v[16:17], v[12:13]
	ds_read_b128 v[12:15], v11 offset:24576
	s_waitcnt lgkmcnt(0)
	v_pk_add_f32 v[8:9], v[8:9], v[14:15]
	v_pk_add_f32 v[16:17], v[16:17], v[12:13]
	ds_read_b128 v[12:15], v11 offset:28672
	s_waitcnt lgkmcnt(0)
	v_pk_add_f32 v[8:9], v[8:9], v[14:15]
	v_or_b32_e32 v14, s27, v196
	v_pk_add_f32 v[16:17], v[16:17], v[12:13]
	v_lshl_add_u64 v[12:13], s[34:35], 0, v[6:7]
	v_lshlrev_b32_e32 v0, 1, v14
	v_lshl_add_u64 v[12:13], v[12:13], 0, v[0:1]
	global_load_dwordx2 v[18:19], v[12:13], off
	v_lshlrev_b32_e32 v12, 2, v14
	global_load_dwordx4 v[12:15], v12, s[6:7]
	v_lshl_add_u64 v[6:7], s[36:37], 0, v[6:7]
	v_lshl_add_u64 v[6:7], v[6:7], 0, v[0:1]
	s_waitcnt vmcnt(0)
	v_pk_add_f32 v[14:15], v[8:9], v[14:15]
	v_pk_add_f32 v[8:9], v[16:17], v[12:13]
	v_lshlrev_b32_e32 v12, 16, v18
	v_mul_f32_e32 v8, 0xbfb8aa3b, v8
	v_exp_f32_e32 v8, v8
	v_mul_f32_e32 v9, 0xbfb8aa3b, v9
	v_exp_f32_e32 v9, v9
	v_mul_f32_e32 v13, 0xbfb8aa3b, v15
	v_add_f32_e32 v8, 1.0, v8
	v_rcp_f32_e32 v8, v8
	v_add_f32_e32 v9, 1.0, v9
	v_rcp_f32_e32 v9, v9
	v_exp_f32_e32 v13, v13
	v_mul_f32_e32 v8, v8, v12
	v_and_b32_e32 v12, 0xffff0000, v18
	v_mul_f32_e32 v9, v9, v12
	v_mul_f32_e32 v12, 0xbfb8aa3b, v14
	v_exp_f32_e32 v12, v12
	v_add_f32_e32 v13, 1.0, v13
	v_rcp_f32_e32 v13, v13
	v_cvt_pk_bf16_f32 v8, v8, v9
	v_add_f32_e32 v12, 1.0, v12
	v_rcp_f32_e32 v12, v12
	v_lshlrev_b32_e32 v9, 16, v19
	v_mul_f32_e32 v9, v12, v9
	v_and_b32_e32 v12, 0xffff0000, v19
	v_mul_f32_e32 v12, v13, v12
	v_cvt_pk_bf16_f32 v9, v9, v12
	global_store_dwordx2 v[6:7], v[8:9], off
	s_branch .LBB0_1624

;     __device__ __forceinline__ float apply(const f32x4 acc, int row, int col, int fq) const {
;         bf16_t* bp = xb + (size_t)row * D + col; const u32x2 r = *(const u32x2*)bp; f32x4 o;
;         o[0] = __uint_as_float(r.x << 16); o[1] = __uint_as_float(r.x & 0xffff0000u); o[2] = __uint_as_float(r.y << 16); o[3] = __uint_as_float(r.y & 0xffff0000u);
;         o += acc * scale;
; template <class SEpi>
; __device__ __forceinline__ void sample_gemm(LAS unsigned char* lds, const bf16_t* A, const bf16_t* Bt, int K, const SEpi& E, int wave, int lane) {
;     ...
;         const int rt = piece >> 4, cg = piece & 15, row = MP + 16 * rt + fr;
;         const bf16_t* ap = A + (size_t)row * K + wave * (K >> 3) + 8 * fq; const bf16_t* bp = Bt + (size_t)(64 * cg + fr) * K + wave * (K >> 3) + 8 * fq;
;         f32x4 acc[4];
; #pragma unroll
;         for (int c = 0; c < 4; ++c) acc[c] = (f32x4){0.f, 0.f, 0.f, 0.f};
; #pragma unroll 1
;         for (int k0 = 0; k0 < nks; k0 += 4) {
;             bf16x8 af[4], bf[4][4];
; #pragma unroll
;             for (int u = 0; u < 4; ++u) { const int ks = (k0 + u < nks) ? k0 + u : k0;
;                 af[u] = *(const bf16x8*)(ap + 32 * ks);
; #pragma unroll
;                 for (int c = 0; c < 4; ++c) bf[u][c] = *(const bf16x8*)(bp + (size_t)(16 * c) * K + 32 * ks); }
; #pragma unroll
;             for (int u = 0; u < 4; ++u) if (k0 + u < nks) {
; #pragma unroll
;                 for (int c = 0; c < 4; ++c) acc[c] = __builtin_amdgcn_mfma_f32_16x16x32_bf16(bf[u][c], af[u], acc[c], 0, 0, 0); }
;         }
;         asm volatile("s_nop 15\n\ts_nop 15" : "+v"(acc[0]), "+v"(acc[1]), "+v"(acc[2]), "+v"(acc[3]));
; #pragma unroll
;         for (int c = 0; c < 4; ++c) red[(wave * 4 + c) * 64 + lane] = acc[c];
;         __syncthreads();
;         if (wave < 4) {
;             f32x4 t = red[wave * 64 + lane];
; #pragma unroll
;             for (int w = 1; w < 8; ++w) t += red[(w * 4 + wave) * 64 + lane];
;             float q = E.apply(t, row, 64 * cg + 16 * wave + 4 * fq, fq);
;             if (SEpi::HAS_SSQ) { q += __shfl_xor(q, 16); q += __shfl_xor(q, 32); if (fq == 0) P[wave * 16 + fr] = q; }
;         }
;         __syncthreads();
;         if (SEpi::HAS_SSQ && wave == 0 && lane < 16) E.ssq_out[(size_t)(MP + 16 * rt + lane) * 16 + cg] = (P[lane] + P[16 + lane]) + (P[32 + lane] + P[48 + lane]);
;         __syncthreads();
.LBB0_1722:
	s_and_b32 s5, s4, 15
	s_lshl_b32 s27, s5, 6
	v_or_b32_e32 v5, s27, v161
	v_lshlrev_b32_e32 v168, 11, v5
	v_lshl_add_u64 v[42:43], v[2:3], 0, v[168:169]
	s_mov_b32 s6, 0x8000
	s_and_b32 s26, s4, -16
	v_add_co_u32_e32 v46, vcc, s6, v42
	s_addk_i32 s26, 0x4000
	s_nop 0
	v_addc_co_u32_e32 v47, vcc, 0, v43, vcc
	s_mov_b32 s6, 0x10000
	v_or_b32_e32 v4, s26, v161
	global_load_dwordx4 v[68:71], v[42:43], off
	v_add_co_u32_e32 v48, vcc, s6, v42
	v_ashrrev_i32_e32 v5, 31, v4
	s_nop 0
	v_addc_co_u32_e32 v49, vcc, 0, v43, vcc
	s_mov_b32 s6, 0x18000
	v_lshlrev_b64 v[4:5], 11, v[4:5]
	v_add_co_u32_e32 v50, vcc, s6, v42
	v_lshl_add_u64 v[44:45], v[0:1], 0, v[4:5]
	s_nop 0
	v_addc_co_u32_e32 v51, vcc, 0, v43, vcc
	global_load_dwordx4 v[72:75], v[44:45], off
	global_load_dwordx4 v[76:79], v[46:47], off
	global_load_dwordx4 v[80:83], v[48:49], off
	global_load_dwordx4 v[84:87], v[42:43], off offset:64
	global_load_dwordx4 v[88:91], v[50:51], off
	global_load_dwordx4 v[92:95], v[44:45], off offset:64
	s_and_b64 vcc, exec, s[46:47]
	global_load_dwordx4 v[96:99], v[48:49], off offset:64
	global_load_dwordx4 v[100:103], v[46:47], off offset:64
	global_load_dwordx4 v[104:107], v[42:43], off offset:128
	global_load_dwordx4 v[108:111], v[44:45], off offset:128
	global_load_dwordx4 v[114:117], v[50:51], off offset:64
	global_load_dwordx4 v[118:121], v[46:47], off offset:128
	global_load_dwordx4 v[122:125], v[48:49], off offset:128
	global_load_dwordx4 v[126:129], v[42:43], off offset:192
	global_load_dwordx4 v[130:133], v[44:45], off offset:192
	global_load_dwordx4 v[134:137], v[50:51], off offset:128
	global_load_dwordx4 v[138:141], v[46:47], off offset:192
	global_load_dwordx4 v[142:145], v[48:49], off offset:192
	global_load_dwordx4 v[146:149], v[50:51], off offset:192
	s_waitcnt vmcnt(0)
	v_mfma_f32_16x16x32_bf16 v[22:25], v[80:83], v[72:75], 0
	v_mfma_f32_16x16x32_bf16 v[10:13], v[68:71], v[72:75], 0
	v_mfma_f32_16x16x32_bf16 v[18:21], v[76:79], v[72:75], 0
	v_mfma_f32_16x16x32_bf16 v[14:17], v[88:91], v[72:75], 0
	v_mfma_f32_16x16x32_bf16 v[10:13], v[84:87], v[92:95], v[10:13]
	v_mfma_f32_16x16x32_bf16 v[18:21], v[100:103], v[92:95], v[18:21]
	v_mfma_f32_16x16x32_bf16 v[22:25], v[96:99], v[92:95], v[22:25]
	v_mfma_f32_16x16x32_bf16 v[10:13], v[104:107], v[108:111], v[10:13]
	v_mfma_f32_16x16x32_bf16 v[14:17], v[114:117], v[92:95], v[14:17]
	v_mfma_f32_16x16x32_bf16 v[18:21], v[118:121], v[108:111], v[18:21]
	v_mfma_f32_16x16x32_bf16 v[22:25], v[122:125], v[108:111], v[22:25]
	v_mfma_f32_16x16x32_bf16 v[10:13], v[126:129], v[130:133], v[10:13]
	v_mfma_f32_16x16x32_bf16 v[14:17], v[134:137], v[108:111], v[14:17]
	v_mfma_f32_16x16x32_bf16 v[18:21], v[138:141], v[130:133], v[18:21]
	v_mfma_f32_16x16x32_bf16 v[22:25], v[142:145], v[130:133], v[22:25]
	v_mfma_f32_16x16x32_bf16 v[14:17], v[146:149], v[130:133], v[14:17]
	s_nop 7
	ds_write_b128 v7, v[10:13]
	s_nop 0
	ds_write_b128 v7, v[18:21] offset:1024
	s_nop 1
	ds_write_b128 v7, v[22:25] offset:2048
	s_nop 1
	ds_write_b128 v7, v[14:17] offset:3072
	s_waitcnt lgkmcnt(0)
	s_barrier
	s_cbranch_vccnz .LBB0_1726
	ds_read_b128 v[10:13], v8
	ds_read_b128 v[14:17], v8 offset:4096
	v_or_b32_e32 v9, s27, v196
	v_lshl_add_u64 v[4:5], s[22:23], 0, v[4:5]
	v_lshlrev_b32_e32 v168, 1, v9
	v_lshl_add_u64 v[4:5], v[4:5], 0, v[168:169]
	s_waitcnt lgkmcnt(0)
	v_pk_add_f32 v[16:17], v[12:13], v[16:17]
	v_pk_add_f32 v[14:15], v[10:11], v[14:15]
	ds_read_b128 v[10:13], v8 offset:8192
	s_waitcnt lgkmcnt(0)
	v_pk_add_f32 v[16:17], v[16:17], v[12:13]
	v_pk_add_f32 v[14:15], v[14:15], v[10:11]
	ds_read_b128 v[10:13], v8 offset:12288
	s_waitcnt lgkmcnt(0)
	v_pk_add_f32 v[16:17], v[16:17], v[12:13]
	v_pk_add_f32 v[14:15], v[14:15], v[10:11]
	ds_read_b128 v[10:13], v8 offset:16384
	s_waitcnt lgkmcnt(0)
	v_pk_add_f32 v[16:17], v[16:17], v[12:13]
	v_pk_add_f32 v[14:15], v[14:15], v[10:11]
	ds_read_b128 v[10:13], v8 offset:20480
	s_waitcnt lgkmcnt(0)
	v_pk_add_f32 v[16:17], v[16:17], v[12:13]
	v_pk_add_f32 v[14:15], v[14:15], v[10:11]
	ds_read_b128 v[10:13], v8 offset:24576
	s_waitcnt lgkmcnt(0)
	v_pk_add_f32 v[16:17], v[16:17], v[12:13]
	v_pk_add_f32 v[14:15], v[14:15], v[10:11]
	ds_read_b128 v[10:13], v8 offset:28672
	s_waitcnt lgkmcnt(0)
	v_pk_add_f32 v[10:11], v[14:15], v[10:11]
	global_load_dwordx2 v[14:15], v[4:5], off
	v_pk_add_f32 v[12:13], v[16:17], v[12:13]
	s_waitcnt vmcnt(0)
	v_lshlrev_b32_e32 v16, 16, v14
	v_and_b32_e32 v17, 0xffff0000, v14
	v_lshlrev_b32_e32 v14, 16, v15
	v_and_b32_e32 v15, 0xffff0000, v15
	v_pk_add_f32 v[12:13], v[12:13], v[14:15]
	v_pk_add_f32 v[10:11], v[10:11], v[16:17]
	s_nop 0
	v_cvt_pk_bf16_f32 v14, v10, v11
	v_cvt_pk_bf16_f32 v15, v12, v13
	global_store_dwordx2 v[4:5], v[14:15], off
	v_mul_f32_e32 v4, v11, v11
	v_mul_f32_e32 v5, v13, v13
	v_fmac_f32_e32 v4, v10, v10
	v_fmac_f32_e32 v5, v12, v12
	v_add_f32_e32 v4, v4, v5
	ds_bpermute_b32 v5, v112, v4
	s_waitcnt lgkmcnt(0)
	v_add_f32_e32 v4, v4, v5
	ds_bpermute_b32 v5, v113, v4
	s_and_saveexec_b64 s[36:37], s[38:39]
	s_cbranch_execz .LBB0_1725
	s_waitcnt lgkmcnt(0)
	v_add_f32_e32 v4, v4, v5
	ds_write_b32 v6, v4 offset:32768

; template <class SEpi>
; __device__ __forceinline__ void sample_gemm(LAS unsigned char* lds, const bf16_t* A, const bf16_t* Bt, int K, const SEpi& E, int wave, int lane) {
;     ...
;         for (int k0 = 0; k0 < nks; k0 += 4) {
;             bf16x8 af[4], bf[4][4];
; #pragma unroll
;             for (int u = 0; u < 4; ++u) { const int ks = (k0 + u < nks) ? k0 + u : k0;
;                 af[u] = *(const bf16x8*)(ap + 32 * ks);
; #pragma unroll
;                 for (int c = 0; c < 4; ++c) bf[u][c] = *(const bf16x8*)(bp + (size_t)(16 * c) * K + 32 * ks); }
; #pragma unroll
;             for (int u = 0; u < 4; ++u) if (k0 + u < nks) {
; #pragma unroll
;                 for (int c = 0; c < 4; ++c) acc[c] = __builtin_amdgcn_mfma_f32_16x16x32_bf16(bf[u][c], af[u], acc[c], 0, 0, 0); }
;         }
.LBB0_1960:
	v_lshl_add_u64 v[26:27], v[22:23], 0, s[34:35]
	v_lshl_add_u64 v[24:25], v[20:21], 0, s[34:35]
	s_mov_b32 s6, 0x3c80000
	v_add_co_u32_e32 v158, vcc, s6, v26
	s_nop 1
	v_addc_co_u32_e32 v159, vcc, 0, v27, vcc
	s_mov_b32 s6, 0x3c96000
	v_add_co_u32_e32 v206, vcc, s6, v26
	s_nop 1
	v_addc_co_u32_e32 v207, vcc, 0, v27, vcc
	s_mov_b32 s6, 0x3cac000
	v_add_co_u32_e32 v208, vcc, s6, v26
	s_nop 1
	v_addc_co_u32_e32 v209, vcc, 0, v27, vcc
	s_mov_b32 s6, 0x3cc2000
	v_add_co_u32_e32 v210, vcc, s6, v26
	s_nop 1
	v_addc_co_u32_e32 v211, vcc, 0, v27, vcc
	global_load_dwordx4 v[32:35], v[24:25], off offset:-128
	global_load_dwordx4 v[36:39], v[158:159], off
	global_load_dwordx4 v[40:43], v[206:207], off
	global_load_dwordx4 v[44:47], v[208:209], off
	global_load_dwordx4 v[48:51], v[210:211], off
	global_load_dwordx4 v[52:55], v[24:25], off offset:-64
	global_load_dwordx4 v[56:59], v[158:159], off offset:64
	global_load_dwordx4 v[60:63], v[206:207], off offset:64
	global_load_dwordx4 v[64:67], v[208:209], off offset:64
	global_load_dwordx4 v[68:71], v[210:211], off offset:64
	global_load_dwordx4 v[72:75], v[24:25], off
	global_load_dwordx4 v[76:79], v[158:159], off offset:128
	global_load_dwordx4 v[80:83], v[206:207], off offset:128
	global_load_dwordx4 v[84:87], v[208:209], off offset:128
	global_load_dwordx4 v[88:91], v[210:211], off offset:128
	global_load_dwordx4 v[92:95], v[24:25], off offset:64
	global_load_dwordx4 v[96:99], v[158:159], off offset:192
	global_load_dwordx4 v[100:103], v[206:207], off offset:192
	global_load_dwordx4 v[104:107], v[208:209], off offset:192
	global_load_dwordx4 v[108:111], v[210:211], off offset:192
	global_load_dwordx4 v[114:117], v[24:25], off offset:128
	global_load_dwordx4 v[118:121], v[158:159], off offset:256
	global_load_dwordx4 v[122:125], v[206:207], off offset:256
	global_load_dwordx4 v[126:129], v[208:209], off offset:256
	global_load_dwordx4 v[130:133], v[210:211], off offset:256
	global_load_dwordx4 v[134:137], v[24:25], off offset:192
	global_load_dwordx4 v[138:141], v[158:159], off offset:320
	global_load_dwordx4 v[142:145], v[206:207], off offset:320
	global_load_dwordx4 v[146:149], v[208:209], off offset:320
	global_load_dwordx4 v[150:153], v[210:211], off offset:320
	global_load_dwordx4 v[154:157], v[24:25], off offset:256
	global_load_dwordx4 v[164:167], v[158:159], off offset:384
	global_load_dwordx4 v[168:171], v[206:207], off offset:384
	global_load_dwordx4 v[172:175], v[208:209], off offset:384
	global_load_dwordx4 v[176:179], v[210:211], off offset:384
	global_load_dwordx4 v[180:183], v[24:25], off offset:320
	global_load_dwordx4 v[184:187], v[158:159], off offset:448
	global_load_dwordx4 v[188:191], v[206:207], off offset:448
	global_load_dwordx4 v[198:201], v[208:209], off offset:448
	global_load_dwordx4 v[202:205], v[210:211], off offset:448
	s_waitcnt vmcnt(35)
	v_mfma_f32_16x16x32_bf16 v[0:3], v[36:39], v[32:35], v[0:3]
	v_mfma_f32_16x16x32_bf16 v[4:7], v[40:43], v[32:35], v[4:7]
	v_mfma_f32_16x16x32_bf16 v[8:11], v[44:47], v[32:35], v[8:11]
	v_mfma_f32_16x16x32_bf16 v[12:15], v[48:51], v[32:35], v[12:15]
	global_load_dwordx4 v[32:35], v[24:25], off offset:384
	global_load_dwordx4 v[36:39], v[158:159], off offset:512
	global_load_dwordx4 v[40:43], v[206:207], off offset:512
	global_load_dwordx4 v[44:47], v[208:209], off offset:512
	global_load_dwordx4 v[48:51], v[210:211], off offset:512
	s_waitcnt vmcnt(35)
	v_mfma_f32_16x16x32_bf16 v[0:3], v[56:59], v[52:55], v[0:3]
	v_mfma_f32_16x16x32_bf16 v[4:7], v[60:63], v[52:55], v[4:7]
	v_mfma_f32_16x16x32_bf16 v[8:11], v[64:67], v[52:55], v[8:11]
	v_mfma_f32_16x16x32_bf16 v[12:15], v[68:71], v[52:55], v[12:15]
	global_load_dwordx4 v[52:55], v[24:25], off offset:448
	global_load_dwordx4 v[56:59], v[158:159], off offset:576
	global_load_dwordx4 v[60:63], v[206:207], off offset:576
	global_load_dwordx4 v[64:67], v[208:209], off offset:576
	global_load_dwordx4 v[68:71], v[210:211], off offset:576
	s_waitcnt vmcnt(35)
	v_mfma_f32_16x16x32_bf16 v[0:3], v[76:79], v[72:75], v[0:3]
	v_mfma_f32_16x16x32_bf16 v[4:7], v[80:83], v[72:75], v[4:7]
	v_mfma_f32_16x16x32_bf16 v[8:11], v[84:87], v[72:75], v[8:11]
	v_mfma_f32_16x16x32_bf16 v[12:15], v[88:91], v[72:75], v[12:15]
	global_load_dwordx4 v[72:75], v[24:25], off offset:512
	global_load_dwordx4 v[76:79], v[158:159], off offset:640
	global_load_dwordx4 v[80:83], v[206:207], off offset:640
	global_load_dwordx4 v[84:87], v[208:209], off offset:640
	global_load_dwordx4 v[88:91], v[210:211], off offset:640
	s_waitcnt vmcnt(35)
	v_mfma_f32_16x16x32_bf16 v[0:3], v[96:99], v[92:95], v[0:3]
	v_mfma_f32_16x16x32_bf16 v[4:7], v[100:103], v[92:95], v[4:7]
	v_mfma_f32_16x16x32_bf16 v[8:11], v[104:107], v[92:95], v[8:11]
	v_mfma_f32_16x16x32_bf16 v[12:15], v[108:111], v[92:95], v[12:15]
	s_waitcnt vmcnt(30)
	v_mfma_f32_16x16x32_bf16 v[0:3], v[118:121], v[114:117], v[0:3]
	v_mfma_f32_16x16x32_bf16 v[4:7], v[122:125], v[114:117], v[4:7]
	v_mfma_f32_16x16x32_bf16 v[8:11], v[126:129], v[114:117], v[8:11]
	v_mfma_f32_16x16x32_bf16 v[12:15], v[130:133], v[114:117], v[12:15]
	s_waitcnt vmcnt(25)
	v_mfma_f32_16x16x32_bf16 v[0:3], v[138:141], v[134:137], v[0:3]
	v_mfma_f32_16x16x32_bf16 v[4:7], v[142:145], v[134:137], v[4:7]
	v_mfma_f32_16x16x32_bf16 v[8:11], v[146:149], v[134:137], v[8:11]
	v_mfma_f32_16x16x32_bf16 v[12:15], v[150:153], v[134:137], v[12:15]
	s_waitcnt vmcnt(20)
	v_mfma_f32_16x16x32_bf16 v[0:3], v[164:167], v[154:157], v[0:3]
	v_mfma_f32_16x16x32_bf16 v[4:7], v[168:171], v[154:157], v[4:7]
	v_mfma_f32_16x16x32_bf16 v[8:11], v[172:175], v[154:157], v[8:11]
	v_mfma_f32_16x16x32_bf16 v[12:15], v[176:179], v[154:157], v[12:15]
	s_waitcnt vmcnt(15)
	v_mfma_f32_16x16x32_bf16 v[0:3], v[184:187], v[180:183], v[0:3]
	v_mfma_f32_16x16x32_bf16 v[4:7], v[188:191], v[180:183], v[4:7]
	v_mfma_f32_16x16x32_bf16 v[8:11], v[198:201], v[180:183], v[8:11]
	v_mfma_f32_16x16x32_bf16 v[12:15], v[202:205], v[180:183], v[12:15]
	s_waitcnt vmcnt(10)
	v_mfma_f32_16x16x32_bf16 v[0:3], v[36:39], v[32:35], v[0:3]
	v_mfma_f32_16x16x32_bf16 v[4:7], v[40:43], v[32:35], v[4:7]
	v_mfma_f32_16x16x32_bf16 v[8:11], v[44:47], v[32:35], v[8:11]
	v_mfma_f32_16x16x32_bf16 v[12:15], v[48:51], v[32:35], v[12:15]
	s_waitcnt vmcnt(5)
	v_mfma_f32_16x16x32_bf16 v[0:3], v[56:59], v[52:55], v[0:3]
	v_mfma_f32_16x16x32_bf16 v[4:7], v[60:63], v[52:55], v[4:7]
	v_mfma_f32_16x16x32_bf16 v[8:11], v[64:67], v[52:55], v[8:11]
	v_mfma_f32_16x16x32_bf16 v[12:15], v[68:71], v[52:55], v[12:15]
	s_waitcnt vmcnt(0)
	v_mfma_f32_16x16x32_bf16 v[0:3], v[76:79], v[72:75], v[0:3]
	v_mfma_f32_16x16x32_bf16 v[4:7], v[80:83], v[72:75], v[4:7]
	v_mfma_f32_16x16x32_bf16 v[8:11], v[84:87], v[72:75], v[8:11]
	v_mfma_f32_16x16x32_bf16 v[12:15], v[88:91], v[72:75], v[12:15]

; __global__ void __launch_bounds__(NTHREADS, 2) fwd_megakernel(Args a) {
	.amdhsa_kernel _Z14fwd_megakernel4Args
		.amdhsa_group_segment_fixed_size 0
		.amdhsa_private_segment_fixed_size 0
		.amdhsa_kernarg_size 472
		.amdhsa_user_sgpr_count 2
		.amdhsa_user_sgpr_dispatch_ptr 0
		.amdhsa_user_sgpr_queue_ptr 0
		.amdhsa_user_sgpr_kernarg_segment_ptr 1
		.amdhsa_user_sgpr_dispatch_id 0
		.amdhsa_user_sgpr_kernarg_preload_length 0
		.amdhsa_user_sgpr_kernarg_preload_offset 0
		.amdhsa_user_sgpr_private_segment_size 0
		.amdhsa_uses_dynamic_stack 0
		.amdhsa_enable_private_segment 0
		.amdhsa_system_sgpr_workgroup_id_x 1
		.amdhsa_system_sgpr_workgroup_id_y 0
		.amdhsa_system_sgpr_workgroup_id_z 0
		.amdhsa_system_sgpr_workgroup_info 0
		.amdhsa_system_vgpr_workitem_id 2
		.amdhsa_next_free_vgpr 256
		.amdhsa_next_free_sgpr 102
		.amdhsa_accum_offset 256
		.amdhsa_reserve_vcc 1
		.amdhsa_float_round_mode_32 0
		.amdhsa_float_round_mode_16_64 0
		.amdhsa_float_denorm_mode_32 3
		.amdhsa_float_denorm_mode_16_64 3
		.amdhsa_dx10_clamp 1
		.amdhsa_ieee_mode 1
		.amdhsa_fp16_overflow 0
		.amdhsa_tg_split 0
		.amdhsa_exception_fp_ieee_invalid_op 0
		.amdhsa_exception_fp_denorm_src 0
		.amdhsa_exception_fp_ieee_div_zero 0
		.amdhsa_exception_fp_ieee_overflow 0
		.amdhsa_exception_fp_ieee_underflow 0
		.amdhsa_exception_fp_ieee_inexact 0
		.amdhsa_exception_int_div_zero 0
	.end_amdhsa_kernel

; __global__ void __launch_bounds__(NTHREADS, 2) fwd_megakernel(Args a) {
amdhsa.kernels:
  - .agpr_count:     0
    .args:
      - .offset:         0
        .size:           216
        .value_kind:     by_value
      - .offset:         216
        .size:           4
        .value_kind:     hidden_block_count_x
      - .offset:         220
        .size:           4
        .value_kind:     hidden_block_count_y
      - .offset:         224
        .size:           4
        .value_kind:     hidden_block_count_z
      - .offset:         228
        .size:           2
        .value_kind:     hidden_group_size_x
      - .offset:         230
        .size:           2
        .value_kind:     hidden_group_size_y
      - .offset:         232
        .size:           2
        .value_kind:     hidden_group_size_z
      - .offset:         234
        .size:           2
        .value_kind:     hidden_remainder_x
      - .offset:         236
        .size:           2
        .value_kind:     hidden_remainder_y
      - .offset:         238
        .size:           2
        .value_kind:     hidden_remainder_z
      - .offset:         256
        .size:           8
        .value_kind:     hidden_global_offset_x
      - .offset:         264
        .size:           8
        .value_kind:     hidden_global_offset_y
      - .offset:         272
        .size:           8
        .value_kind:     hidden_global_offset_z
      - .offset:         280
        .size:           2
        .value_kind:     hidden_grid_dims
      - .offset:         304
        .size:           8
        .value_kind:     hidden_multigrid_sync_arg
      - .offset:         336
        .size:           4
        .value_kind:     hidden_dynamic_lds_size
    .group_segment_fixed_size: 0
    .kernarg_segment_align: 8
    .kernarg_segment_size: 472
    .language:       OpenCL C
    .language_version:
      - 2
      - 0
    .max_flat_workgroup_size: 512
    .name:           _Z14fwd_megakernel4Args
    .private_segment_fixed_size: 0
    .sgpr_count:     108
    .sgpr_spill_count: 81
    .symbol:         _Z14fwd_megakernel4Args.kd
    .uniform_work_group_size: 1
    .uses_dynamic_stack: false
    .vgpr_count:     256
    .vgpr_spill_count: 0
    .wavefront_size: 64
